# speedup vs baseline: 1.0028x; 1.0028x over previous
; DI int crow(int i, int h) { return (i & 3) + 8 * (i >> 2) + 4 * h; }
; DI int tid_half() { return tid_opaque() & 255; }
; DI f32x16 zero16() { f32x16 z; _Pragma("unroll") for (int i = 0; i < 16; ++i) z[i] = 0.f; return z; }
; DI void hgrn_out(const Params& P, int l, int item, char* smem) {
;   const int head = item & 7, c = item >> 3;
;   const int t0 = c * 64;
;   const int tid = tid_half(), lane = tid & 63, w = tid >> 6, r = lane & 31, h = lane >> 5;
;   const int tt = w & 1, dh = w >> 1;
;   float* bs = (float*)smem;
;   float* tot = bs + 64 * BST;
;   float* ssq = tot + 256;
;   const int t = 32 * tt + r;
;   f32x16 o[2]; o[0] = zero16(); o[1] = zero16();
;     ...
;     _Pragma("unroll") for (int st = 0; st < 2; ++st) {
;       _Pragma("unroll") for (int i = 0; i < 16; ++i) {
;         const int s_ = 32 * st + crow(i, h);
;         const bool ok = dir ? (s_ >= t) : (s_ <= t);
;         sc[st][i] = ok ? sc[st][i] : 0.f;
;       }
;     }
.LBB0_734:
	s_mov_b32 s98, 0
	v_writelane_b32 v247, s1, 14
	s_ashr_i32 s2, s3, 3
	v_mov_b32_e32 v1, v144
	v_writelane_b32 v247, s3, 15
	s_lshl_b32 s3, s3, 7
	s_and_b32 s79, s3, 0x380
	v_lshrrev_b32_e32 v0, 1, v1
	s_ashr_i32 s3, s2, 31
	s_lshl_b32 s4, s2, 6
	v_and_b32_e32 v6, 31, v1
	v_bfe_u32 v136, v1, 5, 1
	v_and_b32_e32 v7, 32, v0
	v_and_b32_e32 v0, 0x7f, v1
	s_lshl_b64 s[72:73], s[2:3], 4
	s_movk_i32 s2, 0x80
	v_and_b32_e32 v4, 0xff, v1
	v_bfe_u32 v137, v1, 7, 1
	v_or_b32_e32 v109, v7, v6
	v_lshlrev_b32_e32 v134, 2, v136
	v_bitop3_b32 v1, v1, s2, v203 bitop3:0x6c
	v_lshl_add_u32 v84, v0, 2, s52
	s_movk_i32 s2, 0x4200
	v_mad_u32_u24 v141, v137, s2, v84
	v_cmp_ge_u32_e64 s[2:3], v134, v109
	v_lshl_add_u32 v140, v1, 2, s52
	v_or_b32_e32 v1, 1, v134
	v_writelane_b32 v249, s2, 34
	s_and_b32 s0, s1, 7
	s_ashr_i32 s5, s4, 31
	v_writelane_b32 v249, s3, 35
	v_cmp_le_u32_e64 s[2:3], v134, v109
	s_lshl_b32 s1, s0, 1
	s_lshl_b32 s0, s0, 8
	v_writelane_b32 v247, s2, 16
	v_lshlrev_b32_e32 v80, 5, v137
	v_lshlrev_b32_e32 v135, 6, v137
	v_writelane_b32 v247, s3, 17
	v_cmp_ge_u32_e64 s[2:3], v1, v109
	v_or_b32_e32 v1, 2, v134
	v_or_b32_e32 v2, s4, v80
	v_writelane_b32 v247, s2, 18
	v_lshl_add_u32 v138, v4, 2, s52
	v_or3_b32 v4, v6, s79, v135
	v_writelane_b32 v247, s3, 19
	v_cmp_lt_u32_e64 s[2:3], v134, v109
	v_ashrrev_i32_e32 v3, 31, v2
	v_lshlrev_b32_e32 v152, 3, v136
	v_writelane_b32 v247, s2, 20
	v_lshlrev_b32_e32 v4, 15, v4
	v_lshlrev_b64 v[82:83], 11, v[2:3]
	v_writelane_b32 v247, s3, 21
	v_cmp_ge_u32_e64 s[2:3], v1, v109
	v_mov_b32_e32 v5, v153
	v_or_b32_e32 v32, 24, v134
	v_writelane_b32 v247, s2, 22
	v_or_b32_e32 v33, 25, v134
	v_or_b32_e32 v34, 26, v134
	v_writelane_b32 v247, s3, 23
	v_cmp_le_u32_e64 s[2:3], v1, v109
	v_or_b32_e32 v1, 3, v134
	v_or_b32_e32 v35, 27, v134
	v_writelane_b32 v247, s2, 24
	v_or_b32_e32 v36, 32, v134
	v_or_b32_e32 v37, 33, v134
	v_writelane_b32 v247, s3, 25
	v_cmp_ge_u32_e64 s[2:3], v1, v109
	v_or_b32_e32 v38, 34, v134
	v_or_b32_e32 v39, 35, v134
	v_writelane_b32 v247, s2, 26
	v_or_b32_e32 v40, 40, v134
	v_or_b32_e32 v41, 41, v134
	v_writelane_b32 v247, s3, 27
	v_cmp_le_u32_e64 s[2:3], v1, v109
	v_or_b32_e32 v1, 8, v134
	v_or_b32_e32 v42, 42, v134
	v_writelane_b32 v247, s2, 28
	v_or_b32_e32 v43, 43, v134
	v_or_b32_e32 v44, 48, v134
	v_writelane_b32 v247, s3, 29
	v_cmp_ge_u32_e64 s[2:3], v1, v109
	v_or_b32_e32 v45, 49, v134
	v_or_b32_e32 v46, 50, v134
	v_writelane_b32 v247, s2, 30
	v_or_b32_e32 v47, 51, v134
	v_or_b32_e32 v48, 56, v134
	v_writelane_b32 v247, s3, 31
	v_cmp_le_u32_e64 s[2:3], v1, v109
	v_or_b32_e32 v1, 9, v134
	v_or_b32_e32 v49, 57, v134
	v_writelane_b32 v247, s2, 32
	v_or_b32_e32 v50, 58, v134
	v_or_b32_e32 v51, 59, v134
	v_writelane_b32 v247, s3, 33
	v_cmp_ge_u32_e64 s[2:3], v1, v109
	v_or_b32_e32 v96, 2, v80
	v_or_b32_e32 v98, 4, v80
	v_writelane_b32 v247, s2, 34
	v_or_b32_e32 v100, 6, v80
	v_or_b32_e32 v102, 8, v80
	v_writelane_b32 v247, s3, 35
	v_cmp_le_u32_e64 s[2:3], v1, v109
	v_or_b32_e32 v1, 10, v134
	v_or_b32_e32 v104, 10, v80
	v_writelane_b32 v247, s2, 36
	v_or_b32_e32 v106, 12, v80
	v_or_b32_e32 v108, 14, v80
	v_writelane_b32 v247, s3, 37
	v_cmp_ge_u32_e64 s[2:3], v1, v109
	v_mov_b32_e32 v16, 0
	v_mul_u32_u24_e32 v139, 0x210, v109
	v_writelane_b32 v247, s2, 38
	v_mul_u32_u24_e32 v142, 0x210, v6
	v_mov_b32_e32 v81, v80
	v_writelane_b32 v247, s3, 39
	v_cmp_le_u32_e64 s[2:3], v1, v109
	v_or_b32_e32 v1, 11, v134
	v_mov_b32_e32 v85, v96
	v_writelane_b32 v247, s2, 40
	v_mov_b32_e32 v97, v98
	v_mov_b32_e32 v99, v100
	v_writelane_b32 v247, s3, 41
	v_cmp_ge_u32_e64 s[2:3], v1, v109
	v_mov_b32_e32 v101, v102
	v_mov_b32_e32 v103, v104
	v_writelane_b32 v247, s2, 42
	v_mov_b32_e32 v105, v106
	v_mov_b32_e32 v107, v108
	v_writelane_b32 v247, s3, 43
	v_cmp_le_u32_e64 s[2:3], v1, v109
	v_or_b32_e32 v1, 16, v134
	v_lshl_add_u32 v143, v136, 5, s52
	v_writelane_b32 v247, s2, 44
	s_mov_b32 s76, 0
	v_mov_b32_e32 v17, v16
	v_writelane_b32 v247, s3, 45
	v_cmp_ge_u32_e64 s[2:3], v1, v109
	v_mov_b32_e32 v18, v16
	v_mov_b32_e32 v19, v16
	v_writelane_b32 v247, s2, 46
	v_mov_b32_e32 v20, v16
	v_mov_b32_e32 v21, v16
	v_writelane_b32 v247, s3, 47
	v_cmp_le_u32_e64 s[2:3], v1, v109
	v_or_b32_e32 v1, 17, v134
	v_mov_b32_e32 v22, v16
	v_writelane_b32 v247, s2, 48
	v_mov_b32_e32 v23, v16
; DI int tid_half() { return tid_opaque() & 255; }
; DI f32x16 zero16() { f32x16 z; _Pragma("unroll") for (int i = 0; i < 16; ++i) z[i] = 0.f; return z; }
; DI void hgrn_out(const Params& P, int l, int item, char* smem) {
;   const int head = item & 7, c = item >> 3;
;   const int t0 = c * 64;
;   const int tid = tid_half(), lane = tid & 63, w = tid >> 6, r = lane & 31, h = lane >> 5;
;   const int tt = w & 1, dh = w >> 1;
;   float* bs = (float*)smem;
;   float* tot = bs + 64 * BST;
;   float* ssq = tot + 256;
;   const int t = 32 * tt + r;
;   f32x16 o[2]; o[0] = zero16(); o[1] = zero16();
;   for (int dir = 0; dir < 2; ++dir) {
;     const bf16_t* kk = dir ? P.kb : P.kf;
;     const _Float16* lfn = dir ? P.lfb : P.lff;
;     __syncthreads();
;     {
;       const int dk = tid & 127, hf = tid >> 7;
;       const _Float16* lp = lfn + (size_t)(t0 + 32 * hf) * 1024 + head * 128 + dk;
;       float lv[32];
;       _Pragma("unroll") for (int j = 0; j < 32; ++j) lv[j] = (float)lp[(size_t)j * 1024];
;       float run = 0.f;
;       if (dir == 0) {
;         _Pragma("unroll") for (int i = 0; i < 32; ++i) { run += lv[i]; bs[(32 * hf + i) * BST + dk] = run; }
;       } else {
;         _Pragma("unroll") for (int i = 31; i >= 0; --i) { run += lv[i]; bs[(32 * hf + i) * BST + dk] = run; }
;       }
;       tot[hf * 128 + dk] = run;
;     }
;     __syncthreads();
;     {
;       const int dk = tid & 127, hf = tid >> 7;
;       if (hf == (dir ? 0 : 1)) {
;         const float add = tot[(1 - hf) * 128 + dk];
;         _Pragma("unroll 8") for (int i = 0; i < 32; ++i) bs[(32 * hf + i) * BST + dk] += add;
;       }
;     }
;     __syncthreads();
;     const size_t base = ((size_t)c * 8 + head) * 2 + dir;
;     const bf16_t* stp = P.st + base * 16384;
;     f32x16 sc[2]; sc[0] = zero16(); sc[1] = zero16();
;     _Pragma("unroll 2") for (int ks = 0; ks < 8; ++ks) {
;       const int dk0 = 16 * ks + 8 * h;
;       u32x4 qraw = *(const u32x4*)(P.hq + (size_t)(t0 + t) * 1024 + head * 128 + dk0);
;       float4 bt0 = *(const float4*)(bs + t * BST + dk0), bt1 = *(const float4*)(bs + t * BST + dk0 + 4);
;       float4 rf0 = *(const float4*)(bs + 32 * BST + dk0), rf1 = *(const float4*)(bs + 32 * BST + dk0 + 4);
	v_mov_b32_e32 v24, v16
	v_writelane_b32 v247, s3, 49
	v_cmp_ge_u32_e64 s[2:3], v1, v109
	v_mov_b32_e32 v25, v16
	v_mov_b32_e32 v26, v16
	v_writelane_b32 v247, s2, 50
	v_mov_b32_e32 v27, v16
	v_mov_b32_e32 v28, v16
	v_writelane_b32 v247, s3, 51
	v_cmp_le_u32_e64 s[2:3], v1, v109
	v_or_b32_e32 v1, 18, v134
	v_mov_b32_e32 v29, v16
	v_writelane_b32 v247, s2, 52
	v_mov_b32_e32 v30, v16
	v_mov_b32_e32 v31, v16
	v_writelane_b32 v247, s3, 53
	v_cmp_ge_u32_e64 s[2:3], v1, v109
	v_mov_b32_e32 v8, v16
	v_mov_b32_e32 v9, v16
	v_writelane_b32 v247, s2, 54
	v_mov_b32_e32 v10, v16
	v_mov_b32_e32 v11, v16
	v_writelane_b32 v247, s3, 55
	v_cmp_le_u32_e64 s[2:3], v1, v109
	v_or_b32_e32 v1, 19, v134
	v_cmp_ge_u32_e64 s[6:7], v1, v109
	v_writelane_b32 v247, s2, 56
	v_mov_b32_e32 v12, v16
	v_mov_b32_e32 v13, v16
	v_writelane_b32 v247, s3, 57
	s_lshl_b64 s[2:3], s[4:5], 1
	s_add_u32 s2, s42, s2
	s_addc_u32 s3, s43, s3
	v_writelane_b32 v247, s6, 58
	v_lshl_add_u64 v[2:3], s[2:3], 0, v[152:153]
	v_cmp_le_u32_e64 s[2:3], v1, v109
	v_writelane_b32 v247, s7, 59
	v_or_b32_e32 v152, 0x100000, v4
	v_writelane_b32 v247, s2, 60
	v_lshl_add_u64 v[86:87], v[2:3], 0, v[4:5]
	v_lshl_add_u64 v[88:89], v[2:3], 0, v[152:153]
	v_lshlrev_b32_e32 v1, 4, v136
	v_lshlrev_b32_e32 v2, 8, v6
	v_lshlrev_b32_e32 v3, 14, v137
	v_writelane_b32 v247, s3, 61
	v_cmp_ge_u32_e64 s[2:3], v32, v109
	v_or3_b32 v152, v3, v2, v1
	v_or_b32_e32 v2, s4, v6
	v_writelane_b32 v247, s2, 62
	v_ashrrev_i32_e32 v3, 31, v2
	v_or_b32_e32 v4, 32, v2
	v_writelane_b32 v247, s3, 63
	s_mov_b64 s[2:3], 0x60
	v_lshlrev_b64 v[114:115], 11, v[2:3]
	v_or_b32_e32 v2, v2, v7
	v_lshl_add_u64 v[94:95], v[88:89], 0, s[2:3]
	s_mov_b32 s2, s4
	v_ashrrev_i32_e32 v5, 31, v4
	v_ashrrev_i32_e32 v3, 31, v2
	v_writelane_b32 v246, s2, 0
	v_lshlrev_b64 v[112:113], 11, v[4:5]
	v_lshlrev_b64 v[2:3], 11, v[2:3]
	s_or_b32 s72, s72, s1
	v_writelane_b32 v246, s3, 1
	v_or3_b32 v112, v112, s0, v1
	v_or3_b32 v114, v114, s0, v1
	v_or3_b32 v2, v2, s0, v1
	v_cmp_le_u32_e64 s[0:1], v32, v109
	v_lshl_add_u64 v[90:91], v[88:89], 0, 32
	v_lshl_add_u64 v[92:93], v[88:89], 0, 64
	v_writelane_b32 v246, s0, 2
	v_lshl_add_u64 v[110:111], s[28:29], 0, v[152:153]
	v_lshl_add_u64 v[116:117], s[36:37], 0, v[2:3]
	v_writelane_b32 v246, s1, 3
	v_cmp_ge_u32_e64 s[0:1], v33, v109
	v_lshlrev_b32_e32 v152, 1, v0
	v_mov_b32_e32 v0, v16
	v_writelane_b32 v246, s0, 4
	v_mov_b32_e32 v1, v16
	v_mov_b32_e32 v2, v16
	v_writelane_b32 v246, s1, 5
	v_cmp_le_u32_e64 s[0:1], v33, v109
	v_mov_b32_e32 v3, v16
	v_mov_b32_e32 v4, v16
	v_writelane_b32 v246, s0, 6
	v_mov_b32_e32 v5, v16
	v_mov_b32_e32 v6, v16
	v_writelane_b32 v246, s1, 7
	v_cmp_ge_u32_e64 s[0:1], v34, v109
	v_mov_b32_e32 v7, v16
	v_mov_b32_e32 v14, v16
	v_writelane_b32 v246, s0, 8
	v_mov_b32_e32 v15, v16
	v_cmp_le_u32_e64 s[84:85], v35, v109
	v_writelane_b32 v246, s1, 9
	v_cmp_le_u32_e64 s[0:1], v34, v109
	v_cmp_ge_u32_e64 s[86:87], v36, v109
	v_cmp_le_u32_e64 s[88:89], v36, v109
	v_writelane_b32 v246, s0, 10
	v_cmp_ge_u32_e64 s[90:91], v37, v109
	v_cmp_le_u32_e64 s[92:93], v37, v109
	v_writelane_b32 v246, s1, 11
	v_cmp_ge_u32_e64 s[0:1], v35, v109
	v_cmp_ge_u32_e64 s[94:95], v38, v109
	v_cmp_le_u32_e64 s[96:97], v38, v109
	v_writelane_b32 v246, s0, 12
	v_cmp_ge_u32_e64 s[2:3], v39, v109
	v_cmp_le_u32_e64 s[20:21], v39, v109
	v_writelane_b32 v246, s1, 13
	v_cmp_ge_u32_e64 s[22:23], v40, v109
	v_cmp_le_u32_e64 s[24:25], v40, v109
	v_cmp_ge_u32_e64 s[26:27], v41, v109
	v_cmp_le_u32_e64 s[28:29], v41, v109
	v_cmp_ge_u32_e64 s[30:31], v42, v109
	v_cmp_le_u32_e64 s[34:35], v42, v109
	v_cmp_ge_u32_e64 s[36:37], v43, v109
	v_cmp_le_u32_e64 s[0:1], v43, v109
	v_cmp_ge_u32_e64 s[38:39], v44, v109
	v_cmp_le_u32_e64 s[40:41], v44, v109
	v_cmp_ge_u32_e64 s[42:43], v45, v109
	v_cmp_le_u32_e64 s[44:45], v45, v109
	v_cmp_ge_u32_e64 s[46:47], v46, v109
	v_cmp_le_u32_e64 s[48:49], v46, v109
	v_cmp_ge_u32_e64 s[50:51], v47, v109
	v_cmp_le_u32_e64 s[52:53], v47, v109
	v_cmp_ge_u32_e64 s[54:55], v48, v109
	v_cmp_le_u32_e64 s[56:57], v48, v109
	v_cmp_ge_u32_e64 s[58:59], v49, v109
	v_cmp_le_u32_e64 s[60:61], v49, v109
	v_cmp_ge_u32_e64 s[62:63], v50, v109
	v_cmp_le_u32_e64 s[64:65], v50, v109
	v_cmp_ge_u32_e64 s[66:67], v51, v109
	v_cmp_le_u32_e64 s[68:69], v51, v109
	s_mov_b64 s[74:75], -1

; #define MFMA32(a, b, c) __builtin_amdgcn_mfma_f32_32x32x16_bf16((a), (b), (c), 0, 0, 0)
; DI float bflo(unsigned p) { return __uint_as_float(p << 16); }
; DI float bfhi(unsigned p) { return __uint_as_float(p & 0xffff0000u); }
; DI void hgrn_out(const Params& P, int l, int item, char* smem) {
;     ...
;     _Pragma("unroll 2") for (int ks = 0; ks < 8; ++ks) {
;       const int dk0 = 16 * ks + 8 * h;
;       u32x4 qraw = *(const u32x4*)(P.hq + (size_t)(t0 + t) * 1024 + head * 128 + dk0);
;       float4 bt0 = *(const float4*)(bs + t * BST + dk0), bt1 = *(const float4*)(bs + t * BST + dk0 + 4);
;       float4 rf0 = *(const float4*)(bs + 32 * BST + dk0), rf1 = *(const float4*)(bs + 32 * BST + dk0 + 4);
;       float q0 = bflo(qraw[0]), q1 = bfhi(qraw[0]), q2 = bflo(qraw[1]), q3 = bfhi(qraw[1]);
;       float q4 = bflo(qraw[2]), q5 = bfhi(qraw[2]), q6 = bflo(qraw[3]), q7 = bfhi(qraw[3]);
;       bf16x8 qref = pack8(q0 * __expf(bt0.x - rf0.x), q1 * __expf(bt0.y - rf0.y), q2 * __expf(bt0.z - rf0.z), q3 * __expf(bt0.w - rf0.w),
;                           q4 * __expf(bt1.x - rf1.x), q5 * __expf(bt1.y - rf1.y), q6 * __expf(bt1.z - rf1.z), q7 * __expf(bt1.w - rf1.w));
;       bf16x8 qint = pack8(q0 * __expf(bt0.x), q1 * __expf(bt0.y), q2 * __expf(bt0.z), q3 * __expf(bt0.w),
;                           q4 * __expf(bt1.x), q5 * __expf(bt1.y), q6 * __expf(bt1.z), q7 * __expf(bt1.w));
;       _Pragma("unroll") for (int st = 0; st < 2; ++st) {
;         const int s_ = 32 * st + r;
;         u32x4 kraw = *(const u32x4*)(kk + (size_t)(t0 + s_) * 1024 + head * 128 + dk0);
;         float4 b0 = *(const float4*)(bs + s_ * BST + dk0), b1 = *(const float4*)(bs + s_ * BST + dk0 + 4);
;         bf16x8 kt = pack8(bflo(kraw[0]) * __expf(rf0.x - b0.x), bfhi(kraw[0]) * __expf(rf0.y - b0.y),
;                           bflo(kraw[1]) * __expf(rf0.z - b0.z), bfhi(kraw[1]) * __expf(rf0.w - b0.w),
;                           bflo(kraw[2]) * __expf(rf1.x - b1.x), bfhi(kraw[2]) * __expf(rf1.y - b1.y),
;                           bflo(kraw[3]) * __expf(rf1.z - b1.z), bfhi(kraw[3]) * __expf(rf1.w - b1.w));
;         sc[st] = MFMA32(kt, qref, sc[st]);
;       }
.LBB0_743:
	v_lshl_add_u64 v[226:227], v[116:117], 0, s[76:77]
	v_lshl_add_u64 v[230:231], v[122:123], 0, s[76:77]
	v_lshl_add_u64 v[234:235], v[120:121], 0, s[76:77]
	v_lshl_add_u64 v[238:239], v[118:119], 0, s[76:77]
	global_load_dwordx4 v[206:209], v[226:227], off
	global_load_dwordx4 v[210:213], v[230:231], off
	global_load_dwordx4 v[214:217], v[234:235], off
	global_load_dwordx4 v[218:221], v[238:239], off
	v_add_co_u32_e32 v242, vcc, s33, v238
	s_nop 1
	v_addc_co_u32_e32 v243, vcc, 0, v239, vcc
	global_load_dwordx4 v[222:225], v[242:243], off
	global_load_dwordx4 v[226:229], v[226:227], off offset:32
	global_load_dwordx4 v[230:233], v[230:231], off offset:32
	global_load_dwordx4 v[234:237], v[234:235], off offset:32
	global_load_dwordx4 v[238:241], v[238:239], off offset:32
	global_load_dwordx4 v[242:245], v[242:243], off offset:32
	v_lshl_add_u64 v[132:133], v[116:117], 0, s[76:77]
	v_add_u32_e32 v156, v154, v139
	ds_read_b128 v[76:79], v156
	ds_read_b128 v[124:127], v156 offset:16
	ds_read_b128 v[72:75], v154 offset:16896
	ds_read_b128 v[68:71], v154 offset:16912
	s_waitcnt lgkmcnt(1)
	v_sub_f32_e32 v128, v76, v72
	v_sub_f32_e32 v129, v77, v73
	v_sub_f32_e32 v130, v78, v74
	v_sub_f32_e32 v131, v79, v75
	v_mul_f32_e32 v128, 0x3fb8aa3b, v128
	v_mul_f32_e32 v129, 0x3fb8aa3b, v129
	v_mul_f32_e32 v130, 0x3fb8aa3b, v130
	v_mul_f32_e32 v131, 0x3fb8aa3b, v131
	v_exp_f32_e32 v128, v128
	v_exp_f32_e32 v129, v129
	v_exp_f32_e32 v130, v130
	v_exp_f32_e32 v131, v131
	s_waitcnt lgkmcnt(0)
	v_sub_f32_e32 v155, v124, v68
	v_mul_f32_e32 v76, 0x3fb8aa3b, v76
	v_mul_f32_e32 v155, 0x3fb8aa3b, v155
	v_exp_f32_e32 v162, v76
	v_mul_f32_e32 v76, 0x3fb8aa3b, v77
	v_exp_f32_e32 v158, v155
	v_sub_f32_e32 v155, v125, v69
	v_exp_f32_e32 v163, v76
	v_mul_f32_e32 v155, 0x3fb8aa3b, v155
	v_exp_f32_e32 v159, v155
	v_sub_f32_e32 v155, v126, v70
	v_mul_f32_e32 v155, 0x3fb8aa3b, v155
	v_exp_f32_e32 v160, v155
	v_sub_f32_e32 v155, v127, v71
	v_mul_f32_e32 v155, 0x3fb8aa3b, v155
	v_exp_f32_e32 v161, v155
	v_add_u32_e32 v155, v154, v142
	s_waitcnt vmcnt(9)
	v_lshlrev_b32_e32 v164, 16, v206
	v_and_b32_e32 v165, 0xffff0000, v206
	v_mul_f32_e32 v64, 0x3fb8aa3b, v78
	v_exp_f32_e32 v78, v64
	v_mul_f32_e32 v64, 0x3fb8aa3b, v79
	v_exp_f32_e32 v79, v64
	v_lshlrev_b32_e32 v64, 16, v207
	v_and_b32_e32 v65, 0xffff0000, v207
	v_pk_mul_f32 v[76:77], v[128:129], v[164:165]
	v_pk_mul_f32 v[130:131], v[130:131], v[64:65]
	v_cvt_pk_bf16_f32 v76, v76, v77
	v_cvt_pk_bf16_f32 v77, v130, v131
	v_pk_mul_f32 v[130:131], v[78:79], v[64:65]
	v_mul_f32_e32 v64, 0x3fb8aa3b, v124
	v_mul_f32_e32 v65, 0x3fb8aa3b, v125
	v_exp_f32_e32 v64, v64
	v_exp_f32_e32 v65, v65
	v_lshlrev_b32_e32 v124, 16, v208
	v_and_b32_e32 v125, 0xffff0000, v208
	v_pk_mul_f32 v[78:79], v[158:159], v[124:125]
	v_pk_mul_f32 v[124:125], v[64:65], v[124:125]
	v_mul_f32_e32 v64, 0x3fb8aa3b, v126
	v_mul_f32_e32 v65, 0x3fb8aa3b, v127
	v_exp_f32_e32 v64, v64
	v_exp_f32_e32 v65, v65
	v_lshlrev_b32_e32 v66, 16, v209
	v_and_b32_e32 v67, 0xffff0000, v209
	v_pk_mul_f32 v[126:127], v[160:161], v[66:67]
	v_pk_mul_f32 v[128:129], v[162:163], v[164:165]
	v_cvt_pk_bf16_f32 v78, v78, v79
	v_cvt_pk_bf16_f32 v79, v126, v127
	v_pk_mul_f32 v[126:127], v[64:65], v[66:67]
	v_cvt_pk_bf16_f32 v66, v124, v125
	v_lshl_add_u64 v[124:125], v[122:123], 0, s[76:77]
	v_cvt_pk_bf16_f32 v64, v128, v129
	v_cvt_pk_bf16_f32 v67, v126, v127
	ds_read_b128 v[158:161], v155
	ds_read_b128 v[162:165], v155 offset:16
	v_cvt_pk_bf16_f32 v65, v130, v131
	s_waitcnt lgkmcnt(1)
	v_sub_f32_e32 v130, v72, v158
	v_sub_f32_e32 v131, v73, v159
	v_mul_f32_e32 v130, 0x3fb8aa3b, v130
	v_mul_f32_e32 v131, 0x3fb8aa3b, v131
	v_exp_f32_e32 v130, v130
	v_exp_f32_e32 v131, v131
	s_waitcnt vmcnt(8)
	v_lshlrev_b32_e32 v158, 16, v210
	v_and_b32_e32 v159, 0xffff0000, v210
	v_sub_f32_e32 v126, v74, v160
	v_mul_f32_e32 v126, 0x3fb8aa3b, v126
	v_pk_mul_f32 v[130:131], v[130:131], v[158:159]
	v_exp_f32_e32 v158, v126
	v_sub_f32_e32 v126, v75, v161
	v_mul_f32_e32 v126, 0x3fb8aa3b, v126
	v_exp_f32_e32 v159, v126
	v_lshlrev_b32_e32 v126, 16, v211
	v_and_b32_e32 v127, 0xffff0000, v211
	v_lshlrev_b32_e32 v160, 16, v212
	v_pk_mul_f32 v[158:159], v[158:159], v[126:127]
	s_waitcnt lgkmcnt(0)
	v_sub_f32_e32 v126, v68, v162
	v_sub_f32_e32 v127, v69, v163
	v_mul_f32_e32 v126, 0x3fb8aa3b, v126
	v_mul_f32_e32 v127, 0x3fb8aa3b, v127
	v_exp_f32_e32 v126, v126
	v_exp_f32_e32 v127, v127
	v_and_b32_e32 v161, 0xffff0000, v212
	v_lshlrev_b32_e32 v128, 16, v213
	v_and_b32_e32 v129, 0xffff0000, v213
	v_pk_mul_f32 v[160:161], v[126:127], v[160:161]
	v_sub_f32_e32 v126, v70, v164
	v_sub_f32_e32 v127, v71, v165
	v_mul_f32_e32 v126, 0x3fb8aa3b, v126
	v_mul_f32_e32 v127, 0x3fb8aa3b, v127
	v_exp_f32_e32 v126, v126
	v_exp_f32_e32 v127, v127
	s_nop 0
	v_pk_mul_f32 v[162:163], v[126:127], v[128:129]
	v_cvt_pk_bf16_f32 v126, v130, v131
	v_cvt_pk_bf16_f32 v127, v158, v159
	v_cvt_pk_bf16_f32 v128, v160, v161
	v_cvt_pk_bf16_f32 v129, v162, v163
	s_nop 1
	v_mfma_f32_32x32x16_bf16 v[48:63], v[126:129], v[76:79], v[48:63]
	v_lshl_add_u64 v[126:127], v[120:121], 0, s[76:77]
	ds_read_b128 v[158:161], v155 offset:16896
	ds_read_b128 v[162:165], v155 offset:16912
	s_waitcnt lgkmcnt(1)
	v_sub_f32_e32 v74, v74, v160
	v_sub_f32_e32 v75, v75, v161
	v_mul_f32_e32 v74, 0x3fb8aa3b, v74
	v_mul_f32_e32 v75, 0x3fb8aa3b, v75
	s_waitcnt lgkmcnt(0)
	v_sub_f32_e32 v68, v68, v162
	v_sub_f32_e32 v69, v69, v163
	v_exp_f32_e32 v74, v74
	v_exp_f32_e32 v75, v75
	v_mul_f32_e32 v68, 0x3fb8aa3b, v68
	v_mul_f32_e32 v69, 0x3fb8aa3b, v69
	v_exp_f32_e32 v68, v68
	v_exp_f32_e32 v69, v69
	v_sub_f32_e32 v72, v72, v158
	v_sub_f32_e32 v73, v73, v159
	v_mul_f32_e32 v72, 0x3fb8aa3b, v72
	v_mul_f32_e32 v73, 0x3fb8aa3b, v73
	v_exp_f32_e32 v72, v72
	v_exp_f32_e32 v73, v73
	s_waitcnt vmcnt(7)
; #define MFMA32(a, b, c) __builtin_amdgcn_mfma_f32_32x32x16_bf16((a), (b), (c), 0, 0, 0)
; DI float bflo(unsigned p) { return __uint_as_float(p << 16); }
; DI float bfhi(unsigned p) { return __uint_as_float(p & 0xffff0000u); }
; DI void hgrn_out(const Params& P, int l, int item, char* smem) {
;     ...
;     _Pragma("unroll 2") for (int ks = 0; ks < 8; ++ks) {
;       const int dk0 = 16 * ks + 8 * h;
;       u32x4 qraw = *(const u32x4*)(P.hq + (size_t)(t0 + t) * 1024 + head * 128 + dk0);
;       float4 bt0 = *(const float4*)(bs + t * BST + dk0), bt1 = *(const float4*)(bs + t * BST + dk0 + 4);
;       float4 rf0 = *(const float4*)(bs + 32 * BST + dk0), rf1 = *(const float4*)(bs + 32 * BST + dk0 + 4);
;       float q0 = bflo(qraw[0]), q1 = bfhi(qraw[0]), q2 = bflo(qraw[1]), q3 = bfhi(qraw[1]);
;       float q4 = bflo(qraw[2]), q5 = bfhi(qraw[2]), q6 = bflo(qraw[3]), q7 = bfhi(qraw[3]);
;       bf16x8 qref = pack8(q0 * __expf(bt0.x - rf0.x), q1 * __expf(bt0.y - rf0.y), q2 * __expf(bt0.z - rf0.z), q3 * __expf(bt0.w - rf0.w),
;                           q4 * __expf(bt1.x - rf1.x), q5 * __expf(bt1.y - rf1.y), q6 * __expf(bt1.z - rf1.z), q7 * __expf(bt1.w - rf1.w));
;       bf16x8 qint = pack8(q0 * __expf(bt0.x), q1 * __expf(bt0.y), q2 * __expf(bt0.z), q3 * __expf(bt0.w),
;                           q4 * __expf(bt1.x), q5 * __expf(bt1.y), q6 * __expf(bt1.z), q7 * __expf(bt1.w));
;       _Pragma("unroll") for (int st = 0; st < 2; ++st) {
;         const int s_ = 32 * st + r;
;         u32x4 kraw = *(const u32x4*)(kk + (size_t)(t0 + s_) * 1024 + head * 128 + dk0);
;         float4 b0 = *(const float4*)(bs + s_ * BST + dk0), b1 = *(const float4*)(bs + s_ * BST + dk0 + 4);
;         bf16x8 kt = pack8(bflo(kraw[0]) * __expf(rf0.x - b0.x), bfhi(kraw[0]) * __expf(rf0.y - b0.y),
;                           bflo(kraw[1]) * __expf(rf0.z - b0.z), bfhi(kraw[1]) * __expf(rf0.w - b0.w),
;                           bflo(kraw[2]) * __expf(rf1.x - b1.x), bfhi(kraw[2]) * __expf(rf1.y - b1.y),
;                           bflo(kraw[3]) * __expf(rf1.z - b1.z), bfhi(kraw[3]) * __expf(rf1.w - b1.w));
;         sc[st] = MFMA32(kt, qref, sc[st]);
;       }
;       _Pragma("unroll") for (int mi = 0; mi < 2; ++mi) {
;         const int dv = 32 * (2 * dh + mi) + r;
;         bf16x8 sfr = *(const bf16x8*)(stp + dv * 128 + dk0);
;         o[mi] = MFMA32(sfr, qint, o[mi]);
;       }
	v_lshlrev_b32_e32 v158, 16, v214
	v_and_b32_e32 v159, 0xffff0000, v214
	v_lshlrev_b32_e32 v128, 16, v215
	v_and_b32_e32 v129, 0xffff0000, v215
	v_pk_mul_f32 v[74:75], v[74:75], v[128:129]
	v_lshlrev_b32_e32 v128, 16, v216
	v_and_b32_e32 v129, 0xffff0000, v216
	v_pk_mul_f32 v[128:129], v[68:69], v[128:129]
	v_sub_f32_e32 v68, v70, v164
	v_sub_f32_e32 v69, v71, v165
	v_mul_f32_e32 v68, 0x3fb8aa3b, v68
	v_mul_f32_e32 v69, 0x3fb8aa3b, v69
	v_exp_f32_e32 v68, v68
	v_exp_f32_e32 v69, v69
	v_lshlrev_b32_e32 v70, 16, v217
	v_and_b32_e32 v71, 0xffff0000, v217
	v_pk_mul_f32 v[72:73], v[72:73], v[158:159]
	v_pk_mul_f32 v[130:131], v[68:69], v[70:71]
	v_cvt_pk_bf16_f32 v68, v72, v73
	v_cvt_pk_bf16_f32 v69, v74, v75
	v_cvt_pk_bf16_f32 v70, v128, v129
	v_cvt_pk_bf16_f32 v71, v130, v131
	v_lshl_add_u64 v[130:131], v[118:119], 0, s[76:77]
	v_add_co_u32_e32 v128, vcc, s33, v130
	v_mfma_f32_32x32x16_bf16 v[32:47], v[68:71], v[76:79], v[32:47]
	v_addc_co_u32_e32 v129, vcc, 0, v131, vcc
	s_add_u32 s76, s76, 64
	s_addc_u32 s77, s77, 0
	s_cmpk_eq_i32 s76, 0x100
	s_waitcnt vmcnt(6)
	v_mfma_f32_32x32x16_bf16 v[16:31], v[218:221], v[64:67], v[16:31]
	s_waitcnt vmcnt(5)
	v_mfma_f32_32x32x16_bf16 v[0:15], v[222:225], v[64:67], v[0:15]
	ds_read_b128 v[76:79], v156 offset:64
	ds_read_b128 v[156:159], v156 offset:80
	ds_read_b128 v[72:75], v154 offset:16960
	ds_read_b128 v[68:71], v154 offset:16976
	v_add_u32_e32 v154, 0x80, v154
	s_waitcnt lgkmcnt(1)
	v_sub_f32_e32 v132, v76, v72
	v_sub_f32_e32 v133, v77, v73
	v_sub_f32_e32 v160, v78, v74
	v_sub_f32_e32 v161, v79, v75
	v_mul_f32_e32 v132, 0x3fb8aa3b, v132
	v_mul_f32_e32 v133, 0x3fb8aa3b, v133
	v_mul_f32_e32 v160, 0x3fb8aa3b, v160
	v_mul_f32_e32 v161, 0x3fb8aa3b, v161
	v_exp_f32_e32 v132, v132
	v_exp_f32_e32 v133, v133
	v_exp_f32_e32 v160, v160
	v_exp_f32_e32 v161, v161
	v_mul_f32_e32 v76, 0x3fb8aa3b, v76
	v_exp_f32_e32 v166, v76
	v_mul_f32_e32 v76, 0x3fb8aa3b, v77
	s_waitcnt lgkmcnt(0)
	v_sub_f32_e32 v162, v156, v68
	v_sub_f32_e32 v163, v157, v69
	v_exp_f32_e32 v167, v76
	v_mul_f32_e32 v162, 0x3fb8aa3b, v162
	v_mul_f32_e32 v163, 0x3fb8aa3b, v163
	v_exp_f32_e32 v162, v162
	v_exp_f32_e32 v163, v163
	v_sub_f32_e32 v164, v158, v70
	v_sub_f32_e32 v165, v159, v71
	v_mul_f32_e32 v164, 0x3fb8aa3b, v164
	v_mul_f32_e32 v165, 0x3fb8aa3b, v165
	v_exp_f32_e32 v164, v164
	v_exp_f32_e32 v165, v165
	s_waitcnt vmcnt(4)
	v_lshlrev_b32_e32 v168, 16, v226
	v_and_b32_e32 v169, 0xffff0000, v226
	v_mul_f32_e32 v64, 0x3fb8aa3b, v78
	v_exp_f32_e32 v78, v64
	v_mul_f32_e32 v64, 0x3fb8aa3b, v79
	v_exp_f32_e32 v79, v64
	v_lshlrev_b32_e32 v64, 16, v227
	v_and_b32_e32 v65, 0xffff0000, v227
	v_pk_mul_f32 v[76:77], v[132:133], v[168:169]
	v_pk_mul_f32 v[160:161], v[160:161], v[64:65]
	v_cvt_pk_bf16_f32 v76, v76, v77
	v_cvt_pk_bf16_f32 v77, v160, v161
	v_pk_mul_f32 v[160:161], v[78:79], v[64:65]
	v_mul_f32_e32 v64, 0x3fb8aa3b, v156
	v_mul_f32_e32 v65, 0x3fb8aa3b, v157
	v_exp_f32_e32 v64, v64
	v_exp_f32_e32 v65, v65
	v_lshlrev_b32_e32 v156, 16, v228
	v_and_b32_e32 v157, 0xffff0000, v228
	v_pk_mul_f32 v[78:79], v[162:163], v[156:157]
	v_pk_mul_f32 v[156:157], v[64:65], v[156:157]
	v_mul_f32_e32 v64, 0x3fb8aa3b, v158
	v_mul_f32_e32 v65, 0x3fb8aa3b, v159
	v_exp_f32_e32 v64, v64
	v_exp_f32_e32 v65, v65
	v_lshlrev_b32_e32 v66, 16, v229
	v_and_b32_e32 v67, 0xffff0000, v229
	v_pk_mul_f32 v[158:159], v[164:165], v[66:67]
	v_cvt_pk_bf16_f32 v78, v78, v79
	v_cvt_pk_bf16_f32 v79, v158, v159
	v_pk_mul_f32 v[158:159], v[64:65], v[66:67]
	v_cvt_pk_bf16_f32 v66, v156, v157
	v_cvt_pk_bf16_f32 v67, v158, v159
	v_pk_mul_f32 v[132:133], v[166:167], v[168:169]
	v_cvt_pk_bf16_f32 v65, v160, v161
	ds_read_b128 v[160:163], v155 offset:64
	ds_read_b128 v[164:167], v155 offset:80
	v_cvt_pk_bf16_f32 v64, v132, v133
	s_waitcnt lgkmcnt(1)
	v_sub_f32_e32 v124, v72, v160
	v_sub_f32_e32 v125, v73, v161
	v_mul_f32_e32 v124, 0x3fb8aa3b, v124
	v_mul_f32_e32 v125, 0x3fb8aa3b, v125
	v_exp_f32_e32 v124, v124
	v_exp_f32_e32 v125, v125
	s_waitcnt vmcnt(3)
	v_lshlrev_b32_e32 v132, 16, v230
	v_and_b32_e32 v133, 0xffff0000, v230
	v_pk_mul_f32 v[124:125], v[124:125], v[132:133]
	v_sub_f32_e32 v132, v74, v162
	v_sub_f32_e32 v133, v75, v163
	v_mul_f32_e32 v132, 0x3fb8aa3b, v132
	v_mul_f32_e32 v133, 0x3fb8aa3b, v133
	v_exp_f32_e32 v132, v132
	v_exp_f32_e32 v133, v133
	v_lshlrev_b32_e32 v156, 16, v231
	v_and_b32_e32 v157, 0xffff0000, v231
	v_lshlrev_b32_e32 v160, 16, v232
	v_pk_mul_f32 v[132:133], v[132:133], v[156:157]
	s_waitcnt lgkmcnt(0)
	v_sub_f32_e32 v156, v68, v164
	v_sub_f32_e32 v157, v69, v165
	v_mul_f32_e32 v156, 0x3fb8aa3b, v156
	v_mul_f32_e32 v157, 0x3fb8aa3b, v157
	v_exp_f32_e32 v156, v156
	v_exp_f32_e32 v157, v157
	v_and_b32_e32 v161, 0xffff0000, v232
	v_lshlrev_b32_e32 v158, 16, v233
	v_and_b32_e32 v159, 0xffff0000, v233
	v_pk_mul_f32 v[160:161], v[156:157], v[160:161]
	v_sub_f32_e32 v156, v70, v166
	v_sub_f32_e32 v157, v71, v167
	v_mul_f32_e32 v156, 0x3fb8aa3b, v156
	v_mul_f32_e32 v157, 0x3fb8aa3b, v157
	v_exp_f32_e32 v156, v156
	v_exp_f32_e32 v157, v157
	s_nop 0
	v_pk_mul_f32 v[162:163], v[156:157], v[158:159]
	v_cvt_pk_bf16_f32 v156, v124, v125
	v_cvt_pk_bf16_f32 v157, v132, v133
	v_cvt_pk_bf16_f32 v158, v160, v161
	v_cvt_pk_bf16_f32 v159, v162, v163
	s_waitcnt vmcnt(2)
	v_lshlrev_b32_e32 v132, 16, v234
	v_mfma_f32_32x32x16_bf16 v[48:63], v[156:159], v[76:79], v[48:63]
	ds_read_b128 v[156:159], v155 offset:16960
	ds_read_b128 v[160:163], v155 offset:16976
	v_and_b32_e32 v133, 0xffff0000, v234
	v_lshlrev_b32_e32 v124, 16, v235
	v_and_b32_e32 v125, 0xffff0000, v235
	s_waitcnt lgkmcnt(1)
	v_sub_f32_e32 v74, v74, v158
	v_sub_f32_e32 v75, v75, v159
	v_mul_f32_e32 v74, 0x3fb8aa3b, v74
	v_mul_f32_e32 v75, 0x3fb8aa3b, v75
	s_waitcnt lgkmcnt(0)
	v_sub_f32_e32 v68, v68, v160
	v_sub_f32_e32 v69, v69, v161
	v_exp_f32_e32 v74, v74
	v_exp_f32_e32 v75, v75
	v_mul_f32_e32 v68, 0x3fb8aa3b, v68
	v_mul_f32_e32 v69, 0x3fb8aa3b, v69
	v_exp_f32_e32 v68, v68
	v_exp_f32_e32 v69, v69
	v_pk_mul_f32 v[74:75], v[74:75], v[124:125]
	v_lshlrev_b32_e32 v124, 16, v236
	v_and_b32_e32 v125, 0xffff0000, v236
	v_sub_f32_e32 v72, v72, v156
	v_sub_f32_e32 v73, v73, v157
	v_pk_mul_f32 v[124:125], v[68:69], v[124:125]
	v_sub_f32_e32 v68, v70, v162
	v_sub_f32_e32 v69, v71, v163
	v_mul_f32_e32 v72, 0x3fb8aa3b, v72
	v_mul_f32_e32 v73, 0x3fb8aa3b, v73
	v_mul_f32_e32 v68, 0x3fb8aa3b, v68
	v_mul_f32_e32 v69, 0x3fb8aa3b, v69
	v_exp_f32_e32 v72, v72
	v_exp_f32_e32 v73, v73
	v_exp_f32_e32 v68, v68
	v_exp_f32_e32 v69, v69
	v_lshlrev_b32_e32 v70, 16, v237
	v_and_b32_e32 v71, 0xffff0000, v237
	v_pk_mul_f32 v[72:73], v[72:73], v[132:133]
	v_pk_mul_f32 v[126:127], v[68:69], v[70:71]
	v_cvt_pk_bf16_f32 v68, v72, v73
	v_cvt_pk_bf16_f32 v69, v74, v75
	v_cvt_pk_bf16_f32 v70, v124, v125
	v_cvt_pk_bf16_f32 v71, v126, v127
	s_nop 1
	v_mfma_f32_32x32x16_bf16 v[32:47], v[68:71], v[76:79], v[32:47]
	s_waitcnt vmcnt(1)
	v_mfma_f32_32x32x16_bf16 v[16:31], v[238:241], v[64:67], v[16:31]
	s_waitcnt vmcnt(0)
	v_mfma_f32_32x32x16_bf16 v[0:15], v[242:245], v[64:67], v[0:15]
	s_cbranch_scc0 .LBB0_743
; #define MFMA32(a, b, c) __builtin_amdgcn_mfma_f32_32x32x16_bf16((a), (b), (c), 0, 0, 0)
; DI int crow(int i, int h) { return (i & 3) + 8 * (i >> 2) + 4 * h; }
; DI void hgrn_out(const Params& P, int l, int item, char* smem) {
;     ...
;     _Pragma("unroll") for (int st = 0; st < 2; ++st) {
;       _Pragma("unroll") for (int i = 0; i < 16; ++i) {
;         const int s_ = 32 * st + crow(i, h);
;         const bool ok = dir ? (s_ >= t) : (s_ <= t);
;         sc[st][i] = ok ? sc[st][i] : 0.f;
;       }
;     }
;     _Pragma("unroll") for (int st = 0; st < 2; ++st) {
;       _Pragma("unroll") for (int s2 = 0; s2 < 2; ++s2) {
;         bf16x8 pb = pack8(sc[st][8 * s2], sc[st][8 * s2 + 1], sc[st][8 * s2 + 2], sc[st][8 * s2 + 3],
;                           sc[st][8 * s2 + 4], sc[st][8 * s2 + 5], sc[st][8 * s2 + 6], sc[st][8 * s2 + 7]);
;         _Pragma("unroll") for (int mi = 0; mi < 2; ++mi) {
;           const int dv = 32 * (2 * dh + mi) + r;
;           const bf16_t* vp = P.hvt + (size_t)(head * 128 + dv) * TH + t0 + 32 * st + 16 * s2 + 4 * h;
;           s16x4 lo = *(const s16x4*)vp;
;           s16x4 hi = *(const s16x4*)(vp + 8);
;           bf16x8 va = __builtin_shufflevector(lo, hi, 0, 1, 2, 3, 4, 5, 6, 7);
;           o[mi] = MFMA32(va, pb, o[mi]);
;         }
	s_cmp_lg_u32 s98, 0
	s_cbranch_scc1 .Lhout_vloaded
	global_load_dwordx2 v[170:171], v[86:87], off
	global_load_dwordx2 v[172:173], v[86:87], off offset:16
	global_load_dwordx2 v[174:175], v[88:89], off
	global_load_dwordx2 v[176:177], v[88:89], off offset:16
	global_load_dwordx2 v[178:179], v[86:87], off offset:32
	global_load_dwordx2 v[180:181], v[86:87], off offset:48
	global_load_dwordx2 v[182:183], v[90:91], off
	global_load_dwordx2 v[184:185], v[90:91], off offset:16
	global_load_dwordx2 v[186:187], v[86:87], off offset:64
	global_load_dwordx2 v[188:189], v[86:87], off offset:80
	global_load_dwordx2 v[190:191], v[92:93], off
	global_load_dwordx2 v[192:193], v[92:93], off offset:16
	global_load_dwordx2 v[194:195], v[86:87], off offset:96
	global_load_dwordx2 v[196:197], v[86:87], off offset:112
	global_load_dwordx2 v[252:253], v[94:95], off
	global_load_dwordx2 v[254:255], v[94:95], off offset:16
	s_mov_b32 s98, 1
.Lhout_vloaded:
	v_readlane_b32 s4, v247, 16
	v_readlane_b32 s5, v247, 17
	s_mov_b32 s76, 1
	s_nop 0
	v_cndmask_b32_e64 v64, 0, 1, s[4:5]
	v_readlane_b32 s4, v249, 34
	v_readlane_b32 s5, v249, 35
	s_nop 1
	v_cndmask_b32_e64 v65, 0, 1, s[4:5]
	v_cndmask_b32_e64 v64, v65, v64, s[74:75]
	v_readlane_b32 s4, v247, 20
	v_and_b32_e32 v64, 1, v64
	v_readlane_b32 s5, v247, 21
	v_cmp_eq_u32_e32 vcc, 1, v64
	s_nop 0
	v_cndmask_b32_e64 v64, 0, 1, s[4:5]
	v_readlane_b32 s4, v247, 18
	v_readlane_b32 s5, v247, 19
	v_cndmask_b32_e32 v48, 0, v48, vcc
	s_nop 0
	v_cndmask_b32_e64 v65, 0, 1, s[4:5]
	v_cndmask_b32_e64 v64, v65, v64, s[74:75]
	v_readlane_b32 s4, v247, 24
	v_and_b32_e32 v64, 1, v64
	v_readlane_b32 s5, v247, 25
	v_cmp_eq_u32_e32 vcc, 1, v64
	s_nop 0
	v_cndmask_b32_e64 v64, 0, 1, s[4:5]
	v_readlane_b32 s4, v247, 22
	v_readlane_b32 s5, v247, 23
	v_cndmask_b32_e32 v49, 0, v49, vcc
	s_nop 0
	v_cndmask_b32_e64 v65, 0, 1, s[4:5]
	v_cndmask_b32_e64 v64, v65, v64, s[74:75]
	v_readlane_b32 s4, v247, 28
	v_and_b32_e32 v64, 1, v64
	v_readlane_b32 s5, v247, 29
	v_cmp_eq_u32_e32 vcc, 1, v64
	s_nop 0
	v_cndmask_b32_e64 v64, 0, 1, s[4:5]
	v_readlane_b32 s4, v247, 26
	v_readlane_b32 s5, v247, 27
	v_cndmask_b32_e32 v50, 0, v50, vcc
	s_nop 0
	v_cndmask_b32_e64 v65, 0, 1, s[4:5]
	v_cndmask_b32_e64 v64, v65, v64, s[74:75]
	v_readlane_b32 s4, v247, 32
	v_and_b32_e32 v64, 1, v64
	v_readlane_b32 s5, v247, 33
	v_cmp_eq_u32_e32 vcc, 1, v64
	s_nop 0
	v_cndmask_b32_e64 v64, 0, 1, s[4:5]
	v_readlane_b32 s4, v247, 30
	v_readlane_b32 s5, v247, 31
	v_cndmask_b32_e32 v51, 0, v51, vcc
	s_nop 0
	v_cndmask_b32_e64 v65, 0, 1, s[4:5]
	v_cndmask_b32_e64 v64, v65, v64, s[74:75]
	v_readlane_b32 s4, v247, 36
	v_and_b32_e32 v64, 1, v64
	v_readlane_b32 s5, v247, 37
	v_cmp_eq_u32_e32 vcc, 1, v64
	s_nop 0
	v_cndmask_b32_e64 v64, 0, 1, s[4:5]
	v_readlane_b32 s4, v247, 34
	v_readlane_b32 s5, v247, 35
	v_cndmask_b32_e32 v52, 0, v52, vcc
	s_nop 0
	v_cndmask_b32_e64 v65, 0, 1, s[4:5]
	v_cndmask_b32_e64 v64, v65, v64, s[74:75]
	v_readlane_b32 s4, v247, 40
	v_and_b32_e32 v64, 1, v64
	v_readlane_b32 s5, v247, 41
	v_cmp_eq_u32_e32 vcc, 1, v64
	s_nop 0
	v_cndmask_b32_e64 v64, 0, 1, s[4:5]
	v_readlane_b32 s4, v247, 38
	v_readlane_b32 s5, v247, 39
	v_cndmask_b32_e32 v53, 0, v53, vcc
	s_nop 0
	v_cndmask_b32_e64 v65, 0, 1, s[4:5]
	v_cndmask_b32_e64 v64, v65, v64, s[74:75]
	v_readlane_b32 s4, v247, 44
	v_and_b32_e32 v64, 1, v64
	v_readlane_b32 s5, v247, 45
	v_cmp_eq_u32_e32 vcc, 1, v64
	s_nop 0
	v_cndmask_b32_e64 v64, 0, 1, s[4:5]
	v_readlane_b32 s4, v247, 42
	v_readlane_b32 s5, v247, 43
	v_cndmask_b32_e32 v54, 0, v54, vcc
	s_nop 0
	v_cndmask_b32_e64 v65, 0, 1, s[4:5]
	v_cndmask_b32_e64 v64, v65, v64, s[74:75]
	v_readlane_b32 s4, v247, 48
	v_and_b32_e32 v64, 1, v64
	v_readlane_b32 s5, v247, 49
	v_cmp_eq_u32_e32 vcc, 1, v64
	s_nop 0
	v_cndmask_b32_e64 v64, 0, 1, s[4:5]
	v_readlane_b32 s4, v247, 46
	v_readlane_b32 s5, v247, 47
	v_cndmask_b32_e32 v55, 0, v55, vcc
	s_nop 0
	v_cndmask_b32_e64 v65, 0, 1, s[4:5]
	v_cndmask_b32_e64 v64, v65, v64, s[74:75]
	v_readlane_b32 s4, v247, 52
	v_and_b32_e32 v64, 1, v64
	v_readlane_b32 s5, v247, 53
	v_cmp_eq_u32_e32 vcc, 1, v64
	s_nop 0
	v_cndmask_b32_e64 v64, 0, 1, s[4:5]
	v_readlane_b32 s4, v247, 50
	v_readlane_b32 s5, v247, 51
	v_cndmask_b32_e32 v56, 0, v56, vcc
	s_nop 0
	v_cndmask_b32_e64 v65, 0, 1, s[4:5]
	v_cndmask_b32_e64 v64, v65, v64, s[74:75]
	v_readlane_b32 s4, v247, 56
	v_and_b32_e32 v64, 1, v64
	v_readlane_b32 s5, v247, 57
	v_cmp_eq_u32_e32 vcc, 1, v64
	s_nop 0
	v_cndmask_b32_e64 v64, 0, 1, s[4:5]
	v_readlane_b32 s4, v247, 54
	v_readlane_b32 s5, v247, 55
	v_cndmask_b32_e32 v57, 0, v57, vcc
	s_nop 0
	v_cndmask_b32_e64 v65, 0, 1, s[4:5]
	v_cndmask_b32_e64 v64, v65, v64, s[74:75]
	v_readlane_b32 s4, v247, 60
	v_and_b32_e32 v64, 1, v64
	v_readlane_b32 s5, v247, 61
	v_cmp_eq_u32_e32 vcc, 1, v64
	s_nop 0
	v_cndmask_b32_e64 v64, 0, 1, s[4:5]
	v_readlane_b32 s4, v247, 58
	v_readlane_b32 s5, v247, 59
	v_cndmask_b32_e32 v58, 0, v58, vcc
	s_nop 0
	v_cndmask_b32_e64 v65, 0, 1, s[4:5]
	v_cndmask_b32_e64 v64, v65, v64, s[74:75]
	v_readlane_b32 s4, v246, 2
	v_and_b32_e32 v64, 1, v64
	v_readlane_b32 s5, v246, 3
	v_cmp_eq_u32_e32 vcc, 1, v64
	s_nop 0
	v_cndmask_b32_e64 v64, 0, 1, s[4:5]
	v_readlane_b32 s4, v247, 62
	v_readlane_b32 s5, v247, 63
	v_cndmask_b32_e32 v59, 0, v59, vcc
	s_nop 0
	v_cndmask_b32_e64 v65, 0, 1, s[4:5]
	v_cndmask_b32_e64 v64, v65, v64, s[74:75]
	v_readlane_b32 s4, v246, 6
	v_and_b32_e32 v64, 1, v64
	v_readlane_b32 s5, v246, 7
	v_cmp_eq_u32_e32 vcc, 1, v64
	s_nop 0
	v_cndmask_b32_e64 v64, 0, 1, s[4:5]
	v_readlane_b32 s4, v246, 4
	v_readlane_b32 s5, v246, 5
	v_cndmask_b32_e32 v60, 0, v60, vcc
	s_nop 0
	v_cndmask_b32_e64 v65, 0, 1, s[4:5]
; #define MFMA32(a, b, c) __builtin_amdgcn_mfma_f32_32x32x16_bf16((a), (b), (c), 0, 0, 0)
; DI int crow(int i, int h) { return (i & 3) + 8 * (i >> 2) + 4 * h; }
; DI void hgrn_out(const Params& P, int l, int item, char* smem) {
;     ...
;     _Pragma("unroll") for (int st = 0; st < 2; ++st) {
;       _Pragma("unroll") for (int i = 0; i < 16; ++i) {
;         const int s_ = 32 * st + crow(i, h);
;         const bool ok = dir ? (s_ >= t) : (s_ <= t);
;         sc[st][i] = ok ? sc[st][i] : 0.f;
;       }
;     }
;     _Pragma("unroll") for (int st = 0; st < 2; ++st) {
;       _Pragma("unroll") for (int s2 = 0; s2 < 2; ++s2) {
;         bf16x8 pb = pack8(sc[st][8 * s2], sc[st][8 * s2 + 1], sc[st][8 * s2 + 2], sc[st][8 * s2 + 3],
;                           sc[st][8 * s2 + 4], sc[st][8 * s2 + 5], sc[st][8 * s2 + 6], sc[st][8 * s2 + 7]);
;         _Pragma("unroll") for (int mi = 0; mi < 2; ++mi) {
;           const int dv = 32 * (2 * dh + mi) + r;
;           const bf16_t* vp = P.hvt + (size_t)(head * 128 + dv) * TH + t0 + 32 * st + 16 * s2 + 4 * h;
;           s16x4 lo = *(const s16x4*)vp;
;           s16x4 hi = *(const s16x4*)(vp + 8);
;           bf16x8 va = __builtin_shufflevector(lo, hi, 0, 1, 2, 3, 4, 5, 6, 7);
;           o[mi] = MFMA32(va, pb, o[mi]);
;         }
;       }
;     }
;   }
;   float sq = 0.f;
;   _Pragma("unroll") for (int mi = 0; mi < 2; ++mi) {
;     _Pragma("unroll") for (int i = 0; i < 16; ++i) sq += o[mi][i] * o[mi][i];
;   }
;   sq += __shfl_xor(sq, 32);
;   if (h == 0) ssq[dh * 64 + t] = sq;
	v_cndmask_b32_e64 v64, v65, v64, s[74:75]
	v_readlane_b32 s4, v246, 10
	v_and_b32_e32 v64, 1, v64
	v_readlane_b32 s5, v246, 11
	v_cmp_eq_u32_e32 vcc, 1, v64
	s_nop 0
	v_cndmask_b32_e64 v64, 0, 1, s[4:5]
	v_readlane_b32 s4, v246, 8
	v_readlane_b32 s5, v246, 9
	v_cndmask_b32_e32 v61, 0, v61, vcc
	s_nop 0
	v_cndmask_b32_e64 v65, 0, 1, s[4:5]
	v_cndmask_b32_e64 v64, v65, v64, s[74:75]
	v_readlane_b32 s4, v246, 12
	v_and_b32_e32 v64, 1, v64
	v_readlane_b32 s5, v246, 13
	v_cmp_eq_u32_e32 vcc, 1, v64
	v_cndmask_b32_e64 v64, 0, 1, s[84:85]
	v_cndmask_b32_e64 v65, 0, 1, s[4:5]
	v_cndmask_b32_e64 v64, v65, v64, s[74:75]
	v_and_b32_e32 v64, 1, v64
	v_cndmask_b32_e32 v62, 0, v62, vcc
	v_cmp_eq_u32_e32 vcc, 1, v64
	v_cndmask_b32_e64 v64, 0, 1, s[88:89]
	v_cndmask_b32_e64 v65, 0, 1, s[86:87]
	v_cndmask_b32_e64 v64, v65, v64, s[74:75]
	v_and_b32_e32 v64, 1, v64
	v_cndmask_b32_e32 v63, 0, v63, vcc
	v_cmp_eq_u32_e32 vcc, 1, v64
	v_cndmask_b32_e64 v65, 0, 1, s[90:91]
	s_nop 0
	v_cndmask_b32_e32 v64, 0, v32, vcc
	v_cndmask_b32_e64 v32, 0, 1, s[92:93]
	v_cndmask_b32_e64 v32, v65, v32, s[74:75]
	v_and_b32_e32 v32, 1, v32
	v_cmp_eq_u32_e32 vcc, 1, v32
	v_cndmask_b32_e64 v32, 0, 1, s[96:97]
	s_nop 0
	v_cndmask_b32_e32 v65, 0, v33, vcc
	v_cndmask_b32_e64 v33, 0, 1, s[94:95]
	v_cndmask_b32_e64 v32, v33, v32, s[74:75]
	v_and_b32_e32 v32, 1, v32
	v_cmp_eq_u32_e32 vcc, 1, v32
	v_cndmask_b32_e64 v32, 0, 1, s[20:21]
	v_cndmask_b32_e64 v33, 0, 1, s[2:3]
	v_cndmask_b32_e64 v32, v33, v32, s[74:75]
	v_and_b32_e32 v32, 1, v32
	v_cndmask_b32_e32 v66, 0, v34, vcc
	v_cmp_eq_u32_e32 vcc, 1, v32
	v_cndmask_b32_e64 v32, 0, 1, s[24:25]
	v_cndmask_b32_e64 v33, 0, 1, s[22:23]
	v_cndmask_b32_e64 v32, v33, v32, s[74:75]
	v_and_b32_e32 v32, 1, v32
	v_cndmask_b32_e32 v67, 0, v35, vcc
	v_cmp_eq_u32_e32 vcc, 1, v32
	v_cndmask_b32_e64 v32, 0, 1, s[28:29]
	v_cndmask_b32_e64 v33, 0, 1, s[26:27]
	v_cndmask_b32_e64 v32, v33, v32, s[74:75]
	v_and_b32_e32 v32, 1, v32
	v_cndmask_b32_e32 v68, 0, v36, vcc
	v_cmp_eq_u32_e32 vcc, 1, v32
	v_cndmask_b32_e64 v32, 0, 1, s[34:35]
	v_cndmask_b32_e64 v33, 0, 1, s[30:31]
	v_cndmask_b32_e64 v32, v33, v32, s[74:75]
	v_and_b32_e32 v32, 1, v32
	v_cndmask_b32_e32 v69, 0, v37, vcc
	v_cmp_eq_u32_e32 vcc, 1, v32
	v_cndmask_b32_e64 v32, 0, 1, s[0:1]
	v_cndmask_b32_e64 v33, 0, 1, s[36:37]
	v_cndmask_b32_e64 v32, v33, v32, s[74:75]
	v_and_b32_e32 v32, 1, v32
	v_cndmask_b32_e32 v70, 0, v38, vcc
	v_cmp_eq_u32_e32 vcc, 1, v32
	v_cndmask_b32_e64 v32, 0, 1, s[40:41]
	v_cndmask_b32_e64 v33, 0, 1, s[38:39]
	v_cndmask_b32_e64 v32, v33, v32, s[74:75]
	v_and_b32_e32 v32, 1, v32
	v_cndmask_b32_e32 v71, 0, v39, vcc
	v_cmp_eq_u32_e32 vcc, 1, v32
	v_cndmask_b32_e64 v32, 0, 1, s[44:45]
	v_cndmask_b32_e64 v33, 0, 1, s[42:43]
	v_cndmask_b32_e64 v32, v33, v32, s[74:75]
	v_and_b32_e32 v32, 1, v32
	v_cndmask_b32_e32 v72, 0, v40, vcc
	v_cmp_eq_u32_e32 vcc, 1, v32
	v_cndmask_b32_e64 v32, 0, 1, s[48:49]
	v_cndmask_b32_e64 v33, 0, 1, s[46:47]
	v_cndmask_b32_e64 v32, v33, v32, s[74:75]
	v_and_b32_e32 v32, 1, v32
	v_cndmask_b32_e32 v73, 0, v41, vcc
	v_cmp_eq_u32_e32 vcc, 1, v32
	v_cndmask_b32_e64 v32, 0, 1, s[52:53]
	v_cndmask_b32_e64 v33, 0, 1, s[50:51]
	v_cndmask_b32_e64 v32, v33, v32, s[74:75]
	v_and_b32_e32 v32, 1, v32
	v_cndmask_b32_e32 v74, 0, v42, vcc
	v_cmp_eq_u32_e32 vcc, 1, v32
	v_cndmask_b32_e64 v32, 0, 1, s[56:57]
	v_cndmask_b32_e64 v33, 0, 1, s[54:55]
	v_cndmask_b32_e64 v32, v33, v32, s[74:75]
	v_and_b32_e32 v32, 1, v32
	v_cndmask_b32_e32 v75, 0, v43, vcc
	v_cmp_eq_u32_e32 vcc, 1, v32
	v_cndmask_b32_e64 v32, 0, 1, s[60:61]
	v_cndmask_b32_e64 v33, 0, 1, s[58:59]
	v_cndmask_b32_e64 v32, v33, v32, s[74:75]
	v_and_b32_e32 v32, 1, v32
	v_cndmask_b32_e32 v44, 0, v44, vcc
	v_cmp_eq_u32_e32 vcc, 1, v32
	v_cndmask_b32_e64 v32, 0, 1, s[64:65]
	v_cndmask_b32_e64 v33, 0, 1, s[62:63]
	v_cndmask_b32_e64 v32, v33, v32, s[74:75]
	v_and_b32_e32 v32, 1, v32
	v_cndmask_b32_e32 v45, 0, v45, vcc
	v_cmp_eq_u32_e32 vcc, 1, v32
	v_cndmask_b32_e64 v32, 0, 1, s[68:69]
	v_cndmask_b32_e64 v33, 0, 1, s[66:67]
	v_cndmask_b32_e64 v32, v33, v32, s[74:75]
	v_and_b32_e32 v32, 1, v32
	v_cndmask_b32_e32 v46, 0, v46, vcc
	v_cmp_eq_u32_e32 vcc, 1, v32
	v_cvt_pk_bf16_f32 v40, v48, v49
	v_cvt_pk_bf16_f32 v41, v50, v51
	v_cvt_pk_bf16_f32 v42, v52, v53
	v_cvt_pk_bf16_f32 v43, v54, v55
	v_cndmask_b32_e32 v47, 0, v47, vcc
	s_and_b64 vcc, exec, s[70:71]
	s_waitcnt vmcnt(14)
	v_mfma_f32_32x32x16_bf16 v[16:31], v[170:173], v[40:43], v[16:31]
	s_mov_b64 s[74:75], 0
	s_waitcnt vmcnt(12)
	v_mfma_f32_32x32x16_bf16 v[0:15], v[174:177], v[40:43], v[0:15]
	v_cvt_pk_bf16_f32 v40, v56, v57
	v_cvt_pk_bf16_f32 v41, v58, v59
	v_cvt_pk_bf16_f32 v42, v60, v61
	v_cvt_pk_bf16_f32 v43, v62, v63
	s_nop 0
	s_waitcnt vmcnt(10)
	v_mfma_f32_32x32x16_bf16 v[16:31], v[178:181], v[40:43], v[16:31]
	s_waitcnt vmcnt(8)
	v_mfma_f32_32x32x16_bf16 v[0:15], v[182:185], v[40:43], v[0:15]
	v_cvt_pk_bf16_f32 v40, v64, v65
	v_cvt_pk_bf16_f32 v41, v66, v67
	v_cvt_pk_bf16_f32 v42, v68, v69
	v_cvt_pk_bf16_f32 v43, v70, v71
	s_nop 0
	s_waitcnt vmcnt(6)
	v_mfma_f32_32x32x16_bf16 v[16:31], v[186:189], v[40:43], v[16:31]
	s_waitcnt vmcnt(4)
	v_mfma_f32_32x32x16_bf16 v[0:15], v[190:193], v[40:43], v[0:15]
	v_cvt_pk_bf16_f32 v40, v72, v73
	v_cvt_pk_bf16_f32 v41, v74, v75
	v_cvt_pk_bf16_f32 v42, v44, v45
	v_cvt_pk_bf16_f32 v43, v46, v47
	s_nop 0
	s_waitcnt vmcnt(2)
	v_mfma_f32_32x32x16_bf16 v[16:31], v[194:197], v[40:43], v[16:31]
	s_waitcnt vmcnt(0)
	v_mfma_f32_32x32x16_bf16 v[0:15], v[252:255], v[40:43], v[0:15]
	s_cbranch_vccz .LBB0_735
	s_nop 8
	v_mul_f32_e32 v32, v17, v17
	v_fmac_f32_e32 v32, v16, v16
	v_fmac_f32_e32 v32, v18, v18
	v_fmac_f32_e32 v32, v19, v19
	v_fmac_f32_e32 v32, v20, v20
	v_fmac_f32_e32 v32, v21, v21
	v_fmac_f32_e32 v32, v22, v22
	v_fmac_f32_e32 v32, v23, v23
	v_fmac_f32_e32 v32, v24, v24
	v_fmac_f32_e32 v32, v25, v25
	v_fmac_f32_e32 v32, v26, v26
	v_fmac_f32_e32 v32, v27, v27
	v_fmac_f32_e32 v32, v28, v28
	v_fmac_f32_e32 v32, v29, v29
	v_fmac_f32_e32 v32, v30, v30
	v_fmac_f32_e32 v32, v31, v31
	v_fmac_f32_e32 v32, v0, v0
	v_fmac_f32_e32 v32, v1, v1
	v_fmac_f32_e32 v32, v2, v2
	v_fmac_f32_e32 v32, v3, v3
	v_fmac_f32_e32 v32, v4, v4
	v_fmac_f32_e32 v32, v5, v5
	v_fmac_f32_e32 v32, v6, v6
	v_fmac_f32_e32 v32, v7, v7
	v_fmac_f32_e32 v32, v8, v8
	v_fmac_f32_e32 v32, v9, v9
	v_fmac_f32_e32 v32, v10, v10
	v_fmac_f32_e32 v32, v11, v11
	v_fmac_f32_e32 v32, v12, v12
	v_fmac_f32_e32 v32, v13, v13
	v_cmp_lt_i32_e32 vcc, v199, v198
	v_fmac_f32_e32 v32, v14, v14
	v_fmac_f32_e32 v32, v15, v15
	v_cndmask_b32_e32 v33, v145, v199, vcc
	v_lshlrev_b32_e32 v33, 2, v33
	ds_bpermute_b32 v33, v33, v32
	v_cmp_eq_u32_e32 vcc, 0, v136
	s_and_saveexec_b64 s[0:1], vcc
	v_readlane_b32 s52, v250, 46
	s_cbranch_execz .LBB0_733
	s_waitcnt lgkmcnt(0)
	v_add_f32_e32 v32, v32, v33
	v_lshlrev_b32_e32 v33, 2, v135
	v_lshlrev_b32_e32 v34, 2, v109
	v_add3_u32 v33, s52, v33, v34
	ds_write_b32 v33, v32 offset:34816
	s_branch .LBB0_733

; __global__ void __launch_bounds__(512, 2) fwd_megakernel(Params P) {
;   extern __shared__ __attribute__((aligned(16))) char smem[];
	.amdhsa_kernel _Z14fwd_megakernel6Params
		.amdhsa_group_segment_fixed_size 0
		.amdhsa_private_segment_fixed_size 0
		.amdhsa_kernarg_size 656
		.amdhsa_user_sgpr_count 2
		.amdhsa_user_sgpr_dispatch_ptr 0
		.amdhsa_user_sgpr_queue_ptr 0
		.amdhsa_user_sgpr_kernarg_segment_ptr 1
		.amdhsa_user_sgpr_dispatch_id 0
		.amdhsa_user_sgpr_kernarg_preload_length 0
		.amdhsa_user_sgpr_kernarg_preload_offset 0
		.amdhsa_user_sgpr_private_segment_size 0
		.amdhsa_uses_dynamic_stack 0
		.amdhsa_enable_private_segment 0
		.amdhsa_system_sgpr_workgroup_id_x 1
		.amdhsa_system_sgpr_workgroup_id_y 0
		.amdhsa_system_sgpr_workgroup_id_z 0
		.amdhsa_system_sgpr_workgroup_info 0
		.amdhsa_system_vgpr_workitem_id 2
		.amdhsa_next_free_vgpr 256
		.amdhsa_next_free_sgpr 102
		.amdhsa_accum_offset 256
		.amdhsa_reserve_vcc 1
		.amdhsa_float_round_mode_32 0
		.amdhsa_float_round_mode_16_64 0
		.amdhsa_float_denorm_mode_32 3
		.amdhsa_float_denorm_mode_16_64 3
		.amdhsa_dx10_clamp 1
		.amdhsa_ieee_mode 1
		.amdhsa_fp16_overflow 0
		.amdhsa_tg_split 0
		.amdhsa_exception_fp_ieee_invalid_op 0
		.amdhsa_exception_fp_denorm_src 0
		.amdhsa_exception_fp_ieee_div_zero 0
		.amdhsa_exception_fp_ieee_overflow 0
		.amdhsa_exception_fp_ieee_underflow 0
		.amdhsa_exception_fp_ieee_inexact 0
		.amdhsa_exception_int_div_zero 0
	.end_amdhsa_kernel

; __global__ void __launch_bounds__(512, 2) fwd_megakernel(Params P) {
;   extern __shared__ __attribute__((aligned(16))) char smem[];
.Lfunc_end0:
	.size	_Z14fwd_megakernel6Params, .Lfunc_end0-_Z14fwd_megakernel6Params
	.set _Z14fwd_megakernel6Params.num_vgpr, 256
	.set _Z14fwd_megakernel6Params.num_agpr, 0
	.set _Z14fwd_megakernel6Params.numbered_sgpr, 102
	.set _Z14fwd_megakernel6Params.num_named_barrier, 0
	.set _Z14fwd_megakernel6Params.private_seg_size, 0
	.set _Z14fwd_megakernel6Params.uses_vcc, 1
	.set _Z14fwd_megakernel6Params.uses_flat_scratch, 0
	.set _Z14fwd_megakernel6Params.has_dyn_sized_stack, 0
	.set _Z14fwd_megakernel6Params.has_recursion, 0
	.set _Z14fwd_megakernel6Params.has_indirect_call, 0

; __global__ void __launch_bounds__(512, 2) fwd_megakernel(Params P) {
;   extern __shared__ __attribute__((aligned(16))) char smem[];
amdhsa.kernels:
  - .agpr_count:     0
    .args:
      - .offset:         0
        .size:           400
        .value_kind:     by_value
      - .offset:         400
        .size:           4
        .value_kind:     hidden_block_count_x
      - .offset:         404
        .size:           4
        .value_kind:     hidden_block_count_y
      - .offset:         408
        .size:           4
        .value_kind:     hidden_block_count_z
      - .offset:         412
        .size:           2
        .value_kind:     hidden_group_size_x
      - .offset:         414
        .size:           2
        .value_kind:     hidden_group_size_y
      - .offset:         416
        .size:           2
        .value_kind:     hidden_group_size_z
      - .offset:         418
        .size:           2
        .value_kind:     hidden_remainder_x
      - .offset:         420
        .size:           2
        .value_kind:     hidden_remainder_y
      - .offset:         422
        .size:           2
        .value_kind:     hidden_remainder_z
      - .offset:         440
        .size:           8
        .value_kind:     hidden_global_offset_x
      - .offset:         448
        .size:           8
        .value_kind:     hidden_global_offset_y
      - .offset:         456
        .size:           8
        .value_kind:     hidden_global_offset_z
      - .offset:         464
        .size:           2
        .value_kind:     hidden_grid_dims
      - .offset:         488
        .size:           8
        .value_kind:     hidden_multigrid_sync_arg
      - .offset:         520
        .size:           4
        .value_kind:     hidden_dynamic_lds_size
    .group_segment_fixed_size: 0
    .kernarg_segment_align: 8
    .kernarg_segment_size: 656
    .language:       OpenCL C
    .language_version:
      - 2
      - 0
    .max_flat_workgroup_size: 512
    .name:           _Z14fwd_megakernel6Params
    .private_segment_fixed_size: 0
    .sgpr_count:     108
    .sgpr_spill_count: 292
    .symbol:         _Z14fwd_megakernel6Params.kd
    .uniform_work_group_size: 1
    .uses_dynamic_stack: false
    .vgpr_count:     256
    .vgpr_spill_count: 0
    .wavefront_size: 64
